# glr_pre V^T fragments: odd-token loads become d16_hi loads into the pre-zeroed register (8 loads of a pass in flight before one wait; was 4 serialized trips per pass)
# speedup vs baseline: 1.0180x; 1.0105x over previous
.LBB0_473:
	s_or_b64 exec, exec, s[30:31]
	v_mad_i64_i32 v[2:3], s[30:31], v105, s44, 0
	s_and_saveexec_b64 s[30:31], s[18:19]
	s_cbranch_execz .LBB0_475
	v_lshl_add_u64 v[4:5], v[46:47], 0, v[2:3]
	global_load_short_d16_hi v49, v[4:5], off

.LBB0_477:
	s_or_b64 exec, exec, s[30:31]
	v_mad_i64_i32 v[6:7], s[30:31], v110, s44, 0
	s_and_saveexec_b64 s[30:31], s[16:17]
	s_cbranch_execz .LBB0_479
	v_lshl_add_u64 v[38:39], v[46:47], 0, v[6:7]
	global_load_short_d16_hi v51, v[38:39], off

.LBB0_481:
	s_or_b64 exec, exec, s[30:31]
	v_mad_i64_i32 v[40:41], s[30:31], v117, s44, 0
	s_and_saveexec_b64 s[30:31], s[26:27]
	s_cbranch_execz .LBB0_483
	v_lshl_add_u64 v[42:43], v[46:47], 0, v[40:41]
	global_load_short_d16_hi v53, v[42:43], off

.LBB0_485:
	s_or_b64 exec, exec, s[30:31]
	v_mad_i64_i32 v[44:45], s[30:31], v123, s44, 0
	s_and_saveexec_b64 s[30:31], s[24:25]
	s_cbranch_execz .LBB0_487
	v_lshl_add_u64 v[46:47], v[46:47], 0, v[44:45]
	global_load_short_d16_hi v55, v[46:47], off

.LBB0_489:
	s_or_b64 exec, exec, s[86:87]
	s_and_saveexec_b64 s[14:15], s[18:19]
	s_cbranch_execz .LBB0_491
	v_lshl_add_u64 v[0:1], v[46:47], 0, v[2:3]
	global_load_short_d16_hi v49, v[0:1], off

.LBB0_493:
	s_or_b64 exec, exec, s[14:15]
	s_and_saveexec_b64 s[12:13], s[16:17]
	s_cbranch_execz .LBB0_495
	v_lshl_add_u64 v[2:3], v[46:47], 0, v[6:7]
	global_load_short_d16_hi v1, v[2:3], off

.LBB0_497:
	s_or_b64 exec, exec, s[12:13]
	s_and_saveexec_b64 s[12:13], s[26:27]
	s_cbranch_execz .LBB0_499
	v_lshl_add_u64 v[4:5], v[46:47], 0, v[40:41]
	global_load_short_d16_hi v3, v[4:5], off

.LBB0_501:
	s_or_b64 exec, exec, s[12:13]
	s_and_saveexec_b64 s[12:13], s[24:25]
	s_cbranch_execz .LBB0_503
	v_lshl_add_u64 v[6:7], v[46:47], 0, v[44:45]
	global_load_short_d16_hi v5, v[6:7], off

.LBB0_547:
	s_or_b64 exec, exec, s[30:31]
	s_and_saveexec_b64 s[12:13], s[16:17]
	s_cbranch_execz .LBB0_549
	v_mad_i64_i32 v[4:5], s[16:17], v47, s44, 0
	v_lshl_add_u64 v[4:5], v[0:1], 0, v[4:5]
	global_load_short_d16_hi v3, v[4:5], off

.LBB0_551:
	s_or_b64 exec, exec, s[12:13]
	s_and_saveexec_b64 s[12:13], s[20:21]
	s_cbranch_execz .LBB0_553
	v_mad_i64_i32 v[6:7], s[14:15], v49, s44, 0
	v_lshl_add_u64 v[6:7], v[0:1], 0, v[6:7]
	global_load_short_d16_hi v5, v[6:7], off

.LBB0_555:
	s_or_b64 exec, exec, s[12:13]
	s_and_saveexec_b64 s[12:13], s[22:23]
	s_cbranch_execz .LBB0_557
	v_mad_i64_i32 v[38:39], s[14:15], v51, s44, 0
	v_lshl_add_u64 v[38:39], v[0:1], 0, v[38:39]
	global_load_short_d16_hi v7, v[38:39], off

.LBB0_559:
	s_or_b64 exec, exec, s[12:13]
	s_and_saveexec_b64 s[12:13], s[26:27]
	s_cbranch_execz .LBB0_561
	v_mad_i64_i32 v[40:41], s[14:15], v52, s44, 0
	v_lshl_add_u64 v[0:1], v[0:1], 0, v[40:41]
	global_load_short_d16_hi v39, v[0:1], off

.LBB0_706:
	s_or_b64 exec, exec, s[30:31]
	v_mad_i64_i32 v[6:7], s[30:31], v111, s44, 0
	s_and_saveexec_b64 s[30:31], s[16:17]
	s_cbranch_execz .LBB0_708
	v_lshl_add_u64 v[38:39], v[46:47], 0, v[6:7]
	global_load_short_d16_hi v51, v[38:39], off

.LBB0_710:
	s_or_b64 exec, exec, s[30:31]
	v_mad_i64_i32 v[40:41], s[30:31], v118, s44, 0
	s_and_saveexec_b64 s[30:31], s[26:27]
	s_cbranch_execz .LBB0_712
	v_lshl_add_u64 v[42:43], v[46:47], 0, v[40:41]
	global_load_short_d16_hi v53, v[42:43], off

.LBB0_714:
	s_or_b64 exec, exec, s[30:31]
	v_mad_i64_i32 v[44:45], s[30:31], v124, s44, 0
	s_and_saveexec_b64 s[30:31], s[24:25]
	s_cbranch_execz .LBB0_716
	v_lshl_add_u64 v[46:47], v[46:47], 0, v[44:45]
	global_load_short_d16_hi v55, v[46:47], off
